# P4 row statistics (rstd) computed in the phase prologue so the per-tile cache check always hits (no load round trip in the first epilogue)
# baseline (speedup 1.0000x reference)
; #define PG8_WAIT_V(n) asm volatile("s_waitcnt vmcnt(" #n ")" ::: "memory")
; #define PG8_BAR __builtin_amdgcn_s_barrier()
;     __device__ __forceinline__ void operator()(const f32x4 (&acc)[2][2][4][2], const Unit& u, int wr, int wc, int fr, int fq) const {
;     ...
;                 const size_t row = (size_t)u.pm * 256 + 128 * wr + 64 * ai + 16 * m + fr;
;                 const f32x4* sp = (const f32x4*)(ssq + row * 16);
;                 const f32x4 t = (sp[0] + sp[1]) + (sp[2] + sp[3]);
;                 const float r = __builtin_amdgcn_rsqf(((t[0] + t[1]) + (t[2] + t[3])) * (1.0f / DM) + EPS);
; template <class Epi, class Sched>
; __device__ __forceinline__ void gemm_phase(LAS unsigned char* lds, const Gemm g, const Sched& S, const Epi& E) {
;     ...
;     const char* cA = (const char*)g.A + (size_t)cur.pm * tstep; const char* cB = (const char*)g.Bt + (size_t)cur.pn * tstep;
;     PG8_STAGE(PG8_SB(0, 0), cB, voffB); PG8_STAGE(PG8_SB(0, 1), cB + hstepB, voffB); PG8_STAGE(PG8_SA(0, 0), cA, voffA); PG8_STAGE(PG8_SA(0, 1), cA + hstepA, voffA);
;     if (wr == 1) PG8_BAR;
;     PG8_WAIT_V(2); PG8_BAR;
;     PG8_STAGE(PG8_SB(1, 0), cB + kstep, voffB); PG8_STAGE(PG8_SA(1, 0), cA + kstepA, voffA); PG8_STAGE(PG8_SB(1, 1), cB + hstepB + kstep, voffB);
;     PG8_WAIT_V(6); PG8_BAR;
.LBB0_702:
	v_and_b32_e32 v3, 15, v2
	v_lshrrev_b32_e32 v4, 1, v2
	v_and_b32_e32 v4, 24, v4
	v_lshlrev_b32_e32 v5, 6, v3
	v_lshlrev_b32_e32 v2, 2, v2
	s_and_b32 s5, s0, 3
	v_lshl_or_b32 v5, v4, 1, v5
	s_lshl_b32 s8, s4, 13
	v_and_b32_e32 v2, 32, v2
	v_bitop3_b32 v8, v5, s8, v2 bitop3:0xde
	s_lshl_b32 s5, s5, 12
	v_readlane_b32 s8, v242, 1
	s_lshl_b32 s11, s0, 5
	v_bitop3_b32 v5, v5, s5, v2 bitop3:0xde
	s_waitcnt vmcnt(2)
	s_barrier
	s_add_i32 s26, s35, 0x18000
	v_readlane_b32 s9, v242, 2
	s_mov_b32 m0, s26
	s_nop 0
	global_load_lds_dwordx4 v166, s[8:9]
	s_add_i32 s30, s35, 0x1a000
	s_add_i32 s31, s35, 0x8000
	s_mov_b32 m0, s30
	s_nop 0
	global_load_lds_dwordx4 v168, s[8:9]
	s_add_u32 s8, s6, 0x80
	s_addc_u32 s9, s7, 0
	s_add_i32 s21, s35, 0xa000
	s_add_i32 s23, s35, 0x1c000
	s_add_i32 s22, s35, 0x1e000
	s_add_i32 s24, s35, 0xc000
	s_cmpk_lt_u32 s1, 0x100
	s_cselect_b64 s[98:99], -1, 0
	s_lshl_b32 s1, s4, 7
	v_or_b32_e32 v2, s1, v3
	v_ashrrev_i32_e32 v7, 31, v2
	v_mov_b32_e32 v6, v2
	v_lshlrev_b64 v[144:145], 7, v[6:7]
	v_or_b32_e32 v6, 16, v2
	v_ashrrev_i32_e32 v7, 31, v6
	v_lshlrev_b64 v[146:147], 7, v[6:7]
	v_or_b32_e32 v6, 32, v2
	v_ashrrev_i32_e32 v7, 31, v6
	v_lshlrev_b64 v[148:149], 7, v[6:7]
	v_or_b32_e32 v6, 48, v2
	v_ashrrev_i32_e32 v7, 31, v6
	v_lshlrev_b64 v[150:151], 7, v[6:7]
	v_or_b32_e32 v6, 64, v2
	v_ashrrev_i32_e32 v7, 31, v6
	s_mov_b32 m0, s31
	s_nop 0
	global_load_lds_dwordx4 v165, s[8:9]
	v_lshlrev_b64 v[152:153], 7, v[6:7]
	v_or_b32_e32 v6, 0x50, v2
	s_mov_b32 m0, s21
	s_nop 0
	global_load_lds_dwordx4 v167, s[8:9]
	v_ashrrev_i32_e32 v7, 31, v6
	s_mov_b32 m0, s23
	s_nop 0
	global_load_lds_dwordx4 v166, s[76:77]
	v_lshlrev_b64 v[154:155], 7, v[6:7]
	v_or_b32_e32 v6, 0x60, v2
	s_mov_b32 m0, s22
	s_nop 0
	global_load_lds_dwordx4 v168, s[76:77]
	s_ashr_i32 s4, s1, 31
	v_ashrrev_i32_e32 v7, 31, v6
	s_waitcnt vmcnt(6)
	v_mov_b32_e32 v3, s4
	v_lshlrev_b64 v[156:157], 7, v[6:7]
	v_or_b32_e32 v6, 0x70, v2
	s_bfe_u32 s86, s0, 0x10001
	s_and_b32 s0, s11, 32
	v_ashrrev_i32_e32 v7, 31, v6
	v_lshlrev_b64 v[2:3], 6, v[2:3]
	s_mov_b32 s87, s63
	v_lshlrev_b64 v[158:159], 7, v[6:7]
	v_lshl_add_u64 v[160:161], s[40:41], 0, v[2:3]
	s_lshl_b32 s100, s10, 14
	s_mov_b32 s101, 0
	v_and_b32_e32 v236, 0x30, v0
	v_mov_b32_e32 v237, 0
	v_lshl_add_u64 v[162:163], v[160:161], 0, s[100:101]
	v_mov_b32_e32 v238, 0x1000
	v_mov_b32_e32 v239, 0
	v_lshl_add_u64 v[162:163], v[162:163], 0, v[236:237]
	v_lshl_add_u64 v[238:239], v[162:163], 0, v[238:239]
	global_load_dwordx4 v[172:175], v[162:163], off
	global_load_dwordx4 v[176:179], v[162:163], off offset:1024
	global_load_dwordx4 v[180:183], v[162:163], off offset:2048
	global_load_dwordx4 v[184:187], v[162:163], off offset:3072
	global_load_dwordx4 v[188:191], v[238:239], off
	global_load_dwordx4 v[192:195], v[238:239], off offset:1024
	global_load_dwordx4 v[196:199], v[238:239], off offset:2048
	global_load_dwordx4 v[200:203], v[238:239], off offset:3072
	s_waitcnt vmcnt(0)
	v_add_f32_e32 v172, v172, v173
	v_add_f32_e32 v176, v176, v177
	v_add_f32_e32 v180, v180, v181
	v_add_f32_e32 v184, v184, v185
	v_add_f32_e32 v188, v188, v189
	v_add_f32_e32 v192, v192, v193
	v_add_f32_e32 v196, v196, v197
	v_add_f32_e32 v200, v200, v201
	v_add_f32_e32 v174, v174, v175
	v_add_f32_e32 v178, v178, v179
	v_add_f32_e32 v182, v182, v183
	v_add_f32_e32 v186, v186, v187
	v_add_f32_e32 v190, v190, v191
	v_add_f32_e32 v194, v194, v195
	v_add_f32_e32 v198, v198, v199
	v_add_f32_e32 v202, v202, v203
	v_add_f32_e32 v172, v172, v174
	v_add_f32_e32 v176, v176, v178
	v_add_f32_e32 v180, v180, v182
	v_add_f32_e32 v184, v184, v186
	v_add_f32_e32 v188, v188, v190
	v_add_f32_e32 v192, v192, v194
	v_add_f32_e32 v196, v196, v198
	v_add_f32_e32 v200, v200, v202
	v_mov_b32_e32 v173, v172
	v_mov_b32_e32 v177, v176
	v_mov_b32_e32 v181, v180
	v_mov_b32_e32 v185, v184
	v_mov_b32_e32 v189, v188
	v_mov_b32_e32 v193, v192
	v_mov_b32_e32 v197, v196
	v_mov_b32_e32 v201, v200
	v_permlane16_swap_b32_e32 v172, v173
	v_permlane16_swap_b32_e32 v176, v177
	v_permlane16_swap_b32_e32 v180, v181
	v_permlane16_swap_b32_e32 v184, v185
	v_permlane16_swap_b32_e32 v188, v189
	v_permlane16_swap_b32_e32 v192, v193
	v_permlane16_swap_b32_e32 v196, v197
	v_permlane16_swap_b32_e32 v200, v201
	v_add_f32_e32 v172, v172, v173
	v_add_f32_e32 v176, v176, v177
	v_add_f32_e32 v180, v180, v181
	v_add_f32_e32 v184, v184, v185
	v_add_f32_e32 v188, v188, v189
	v_add_f32_e32 v192, v192, v193
	v_add_f32_e32 v196, v196, v197
	v_add_f32_e32 v200, v200, v201
	v_mov_b32_e32 v173, v172
	v_mov_b32_e32 v177, v176
	v_mov_b32_e32 v181, v180
	v_mov_b32_e32 v185, v184
	v_mov_b32_e32 v189, v188
	v_mov_b32_e32 v193, v192
	v_mov_b32_e32 v197, v196
	v_mov_b32_e32 v201, v200
	v_permlane32_swap_b32_e32 v172, v173
	v_permlane32_swap_b32_e32 v176, v177
	v_permlane32_swap_b32_e32 v180, v181
	v_permlane32_swap_b32_e32 v184, v185
	v_permlane32_swap_b32_e32 v188, v189
	v_permlane32_swap_b32_e32 v192, v193
	v_permlane32_swap_b32_e32 v196, v197
	v_permlane32_swap_b32_e32 v200, v201
	v_add_f32_e32 v172, v172, v173
	v_add_f32_e32 v176, v176, v177
	v_add_f32_e32 v180, v180, v181
	v_add_f32_e32 v184, v184, v185
	v_add_f32_e32 v188, v188, v189
	v_add_f32_e32 v192, v192, v193
	v_add_f32_e32 v196, v196, v197
	v_add_f32_e32 v200, v200, v201
	v_fmamk_f32 v172, v172, 0x3a800000, v1
	v_fmamk_f32 v176, v176, 0x3a800000, v1
	v_fmamk_f32 v180, v180, 0x3a800000, v1
	v_fmamk_f32 v184, v184, 0x3a800000, v1
	v_fmamk_f32 v188, v188, 0x3a800000, v1
	v_fmamk_f32 v192, v192, 0x3a800000, v1
	v_fmamk_f32 v196, v196, 0x3a800000, v1
	v_fmamk_f32 v200, v200, 0x3a800000, v1
	v_rsq_f32_e32 v244, v172
	v_rsq_f32_e32 v245, v176
	v_rsq_f32_e32 v246, v180
	v_rsq_f32_e32 v247, v184
	v_rsq_f32_e32 v248, v188
	v_rsq_f32_e32 v249, v192
	v_rsq_f32_e32 v250, v196
	v_rsq_f32_e32 v251, v200
	s_mov_b32 s28, 0
	v_add_u32_e32 v169, 0, v5
	v_add_u32_e32 v170, 0, v8
	s_lshl_b32 s62, s0, 1
	v_lshlrev_b32_e32 v134, 1, v4
	v_readlane_b32 s29, v243, 26
	s_mov_b64 s[14:15], s[70:71]
	s_barrier
	s_branch .LBB0_705
